# v81 + g4: S4 unit's first-body vmcnt guards 1-2 leave the previous epilogue's stores in the outstanding window (vmcnt 8 -> 16/20), acks due at guard 3
# baseline (speedup 1.0000x reference)
.LBB0_985:
	v_readlane_b32 s34, v246, 2
	v_readlane_b32 s35, v246, 3
	s_add_u32 s26, s34, 0xf800000
	s_mov_b64 s[28:29], 0x80
	s_addc_u32 s27, s35, 0
	s_and_b32 s4, s3, 3
	s_add_i32 m0, s54, 0x18000
	v_lshl_add_u64 v[8:9], v[8:9], 0, s[28:29]
	s_lshl_b32 s58, s33, 1
	s_lshl_b32 s5, s1, 13
	s_lshl_b32 s7, s4, 12
	s_and_b32 s59, s2, -2
	global_load_lds_dwordx4 v[8:9], off
	v_lshl_add_u64 v[6:7], v[6:7], 0, s[28:29]
	s_add_i32 m0, s54, 0x1a000
	s_add_i32 s60, s54, 0x8000
	s_add_i32 s61, s54, 0xa000
	global_load_lds_dwordx4 v[6:7], off
	v_lshl_add_u64 v[2:3], v[2:3], 0, s[28:29]
	s_mov_b32 m0, s60
	s_add_u32 s2, s10, 0x40080
	global_load_lds_dwordx4 v[2:3], off
	v_lshl_add_u64 v[2:3], v[4:5], 0, s[28:29]
	s_mov_b32 m0, s61
	s_addc_u32 s3, s11, 0
	global_load_lds_dwordx4 v[2:3], off
	s_add_i32 m0, s54, 0x1c000
	v_lshl_add_u64 v[2:3], s[2:3], 0, v[184:185]
	global_load_lds_dwordx4 v[2:3], off
	v_lshl_add_u64 v[2:3], s[2:3], 0, v[188:189]
	s_add_i32 m0, s54, 0x1e000
	v_and_b32_e32 v179, 15, v0
	global_load_lds_dwordx4 v[2:3], off
	s_waitcnt vmcnt(8)
	s_barrier
	v_bfe_u32 v2, v0, 4, 2
	v_lshl_or_b32 v212, s1, 6, v179
	v_lshlrev_b32_e32 v3, 3, v2
	v_lshlrev_b32_e32 v2, 4, v2
	v_lshlrev_b32_e32 v6, 6, v0
	s_movk_i32 s1, 0x3c0
	s_cmpk_lt_u32 s0, 0x100
	v_and_or_b32 v6, v6, s1, v2
	s_cselect_b64 s[30:31], -1, 0
	s_and_b32 s0, s0, 0xffffff00
	s_lshl_b32 s1, s4, 6
	v_lshl_or_b32 v214, s4, 5, v3
	s_or_b32 s0, s1, s0
	v_mov_b32_e32 v3, v185
	v_lshl_or_b32 v4, v179, 6, v2
	v_or3_b32 v215, s0, v2, v179
	v_lshl_add_u64 v[2:3], s[34:35], 0, v[2:3]
	s_mov_b64 s[0:1], 0x1bb00000
	v_lshl_add_u64 v[190:191], v[2:3], 0, s[0:1]
	v_lshlrev_b32_e32 v2, 8, v0
	v_and_b32_e32 v2, 0x18000, v2
	v_lshlrev_b32_e32 v3, 11, v12
	v_or3_b32 v2, v10, v2, v3
	v_add_u32_e32 v192, v2, v11
	v_lshlrev_b32_e32 v2, 4, v13
	v_and_b32_e32 v2, 0x38000, v2
	v_and_b32_e32 v5, 32, v180
	s_waitcnt vmcnt(6)
	s_add_u32 s34, s34, 0x3e40
	v_or3_b32 v2, v10, v2, v3
	v_bitop3_b32 v4, v4, s5, v5 bitop3:0xde
	v_bitop3_b32 v213, s7, v6, v5 bitop3:0xf6
	s_addc_u32 s35, s35, 0
	v_add_u32_e32 v194, v2, v11
	s_add_i32 s62, 0, 0x10000
	s_add_i32 s63, 0, 0x14000
	v_mbcnt_lo_u32_b32 v2, -1, 0
	v_lshrrev_b32_e32 v1, 4, v0
	v_add_u32_e32 v216, 0x200, v215
	v_add_u32_e32 v217, 0x400, v215
	v_add_u32_e32 v218, 0x600, v215
	v_mov_b32_e32 v193, v185
	v_mov_b32_e32 v195, v185
	v_add_u32_e32 v219, s62, v213
	v_add_u32_e32 v220, s63, v213
	v_add_u32_e32 v221, 0, v4
	s_movk_i32 s64, 0x80
	s_movk_i32 s65, 0x1550
	s_movk_i32 s66, 0x154f
	s_movk_i32 s67, 0xfb10
	v_mbcnt_hi_u32_b32 v181, -1, v2
	v_mov_b32_e32 v222, 0x358637bd
	s_movk_i32 s68, 0x1600
	s_mov_b32 s69, 0x34a0000
	s_add_i32 s70, 0, 0x201ac
	s_mov_b32 s0, s52
	s_mov_b32 s72, 0
	s_waitcnt vmcnt(8)
	v_add_f32_e32 v114, v114, v115
	v_add_f32_e32 v116, v116, v117
	v_add_f32_e32 v118, v118, v119
	v_add_f32_e32 v120, v120, v121
	v_add_f32_e32 v122, v122, v123
	v_add_f32_e32 v124, v124, v125
	v_add_f32_e32 v126, v126, v127
	v_add_f32_e32 v128, v128, v129
	v_add_f32_e32 v114, v114, v116
	v_add_f32_e32 v118, v118, v120
	v_add_f32_e32 v122, v122, v124
	v_add_f32_e32 v126, v126, v128
	v_add_f32_e32 v114, v114, v118
	v_add_f32_e32 v122, v122, v126
	v_add_f32_e32 v114, v114, v122
	v_fmamk_f32 v114, v114, 0x3a800000, v222
	v_rsq_f32_e32 v114, v114
	v_mov_b32_e32 v131, 0x21000
	v_lshl_add_u32 v131, v0, 2, v131
	ds_write_b32 v131, v114
	s_waitcnt lgkmcnt(0)
	s_barrier
	s_mov_b32 s101, 0
	s_branch .LBB0_988

.LBB0_991:
	ds_read_b128 v[66:69], v219
	ds_read_b128 v[70:73], v219 offset:1024
	ds_read_b128 v[86:89], v219 offset:2048
	ds_read_b128 v[106:109], v219 offset:3072
	ds_read_b128 v[146:149], v220
	ds_read_b128 v[150:153], v220 offset:1024
	ds_read_b128 v[154:157], v220 offset:2048
	ds_read_b128 v[158:161], v220 offset:3072
	s_add_u32 s10, s8, 0xfffc0080
	s_addc_u32 s11, s9, -1
	s_cmp_eq_u32 s22, 12
	s_cselect_b32 s45, s1, s11
	s_cselect_b32 s44, s2, s10
	s_cselect_b32 s11, s3, s7
	s_cselect_b32 s10, s4, s5
	s_add_i32 m0, s54, 0xc000
	ds_read_b128 v[162:165], v221
	ds_read_b128 v[166:169], v221 offset:1024
	ds_read_b128 v[170:173], v221 offset:2048
	ds_read_b128 v[174:177], v221 offset:3072
	ds_read_b128 v[196:199], v221 offset:4096
	ds_read_b128 v[200:203], v221 offset:5120
	ds_read_b128 v[204:207], v221 offset:6144
	ds_read_b128 v[208:211], v221 offset:7168
	global_load_lds_dwordx4 v192, s[8:9]
	s_add_i32 m0, s54, 0xe000
	s_nop 0
	global_load_lds_dwordx4 v194, s[8:9]
	s_cmp_eq_u32 s101, 0
	s_cbranch_scc1 .Lg4x_a
	s_cmp_eq_u32 s101, 1
	s_cbranch_scc1 .Lg4x_b
	s_waitcnt vmcnt(20)
	s_branch .Lg4x_d
.Lg4x_b:
	s_waitcnt vmcnt(16)
	s_branch .Lg4x_d

.Lg4x_d:
	s_waitcnt lgkmcnt(0)
	s_barrier
	s_setprio 1
	s_waitcnt lgkmcnt(0)
	v_mfma_f32_16x16x32_bf16 v[142:145], v[66:69], v[162:165], v[142:145]
	v_mfma_f32_16x16x32_bf16 v[134:137], v[86:89], v[162:165], v[134:137]
	v_mfma_f32_16x16x32_bf16 v[126:129], v[66:69], v[170:173], v[126:129]
	v_mfma_f32_16x16x32_bf16 v[122:125], v[86:89], v[170:173], v[122:125]
	v_mfma_f32_16x16x32_bf16 v[110:113], v[66:69], v[196:199], v[110:113]
	v_mfma_f32_16x16x32_bf16 v[102:105], v[86:89], v[196:199], v[102:105]
	v_mfma_f32_16x16x32_bf16 v[90:93], v[66:69], v[204:207], v[90:93]
	v_mfma_f32_16x16x32_bf16 v[82:85], v[86:89], v[204:207], v[82:85]
	v_mfma_f32_16x16x32_bf16 v[142:145], v[70:73], v[166:169], v[142:145]
	v_mfma_f32_16x16x32_bf16 v[134:137], v[106:109], v[166:169], v[134:137]
	v_mfma_f32_16x16x32_bf16 v[126:129], v[70:73], v[174:177], v[126:129]
	v_mfma_f32_16x16x32_bf16 v[122:125], v[106:109], v[174:177], v[122:125]
	v_mfma_f32_16x16x32_bf16 v[110:113], v[70:73], v[200:203], v[110:113]
	v_mfma_f32_16x16x32_bf16 v[102:105], v[106:109], v[200:203], v[102:105]
	v_mfma_f32_16x16x32_bf16 v[90:93], v[70:73], v[208:211], v[90:93]
	v_mfma_f32_16x16x32_bf16 v[82:85], v[106:109], v[208:211], v[82:85]
	s_setprio 0
	s_setprio 1
	v_mfma_f32_16x16x32_bf16 v[138:141], v[146:149], v[162:165], v[138:141]
	v_mfma_f32_16x16x32_bf16 v[130:133], v[154:157], v[162:165], v[130:133]
	v_mfma_f32_16x16x32_bf16 v[118:121], v[146:149], v[170:173], v[118:121]
	v_mfma_f32_16x16x32_bf16 v[114:117], v[154:157], v[170:173], v[114:117]
	v_mfma_f32_16x16x32_bf16 v[98:101], v[146:149], v[196:199], v[98:101]
	v_mfma_f32_16x16x32_bf16 v[94:97], v[154:157], v[196:199], v[94:97]
	v_mfma_f32_16x16x32_bf16 v[78:81], v[146:149], v[204:207], v[78:81]
	v_mfma_f32_16x16x32_bf16 v[74:77], v[154:157], v[204:207], v[74:77]
	v_mfma_f32_16x16x32_bf16 v[138:141], v[150:153], v[166:169], v[138:141]
	v_mfma_f32_16x16x32_bf16 v[130:133], v[158:161], v[166:169], v[130:133]
	v_mfma_f32_16x16x32_bf16 v[118:121], v[150:153], v[174:177], v[118:121]
	v_mfma_f32_16x16x32_bf16 v[114:117], v[158:161], v[174:177], v[114:117]
	v_mfma_f32_16x16x32_bf16 v[98:101], v[150:153], v[200:203], v[98:101]
	v_mfma_f32_16x16x32_bf16 v[94:97], v[158:161], v[200:203], v[94:97]
	v_mfma_f32_16x16x32_bf16 v[78:81], v[150:153], v[208:211], v[78:81]
	v_mfma_f32_16x16x32_bf16 v[74:77], v[158:161], v[208:211], v[74:77]
	s_setprio 0
	s_barrier
	s_add_i32 s37, s62, s53
	s_mov_b32 m0, s37
	ds_read_b128 v[162:165], v221 offset:16384
	ds_read_b128 v[166:169], v221 offset:17408
	ds_read_b128 v[170:173], v221 offset:18432
	ds_read_b128 v[174:177], v221 offset:19456
	ds_read_b128 v[196:199], v221 offset:20480
	ds_read_b128 v[200:203], v221 offset:21504
	ds_read_b128 v[204:207], v221 offset:22528
	ds_read_b128 v[208:211], v221 offset:23552
	global_load_lds_dwordx4 v184, s[10:11]
	s_add_i32 m0, s37, 0x2000
	s_add_u32 s46, s10, 0x40000
	s_addc_u32 s47, s11, 0
	s_add_i32 s37, s63, s53
	global_load_lds_dwordx4 v188, s[10:11]
	s_mov_b32 m0, s37
	s_nop 0
	global_load_lds_dwordx4 v184, s[46:47]
	s_add_i32 m0, s37, 0x2000
	s_nop 0
	global_load_lds_dwordx4 v188, s[46:47]
	s_mov_b32 m0, s54
	s_nop 0
	global_load_lds_dwordx4 v182, s[44:45]
	s_mov_b32 m0, s55
	s_nop 0
	global_load_lds_dwordx4 v186, s[44:45]
	s_cmp_eq_u32 s101, 0
	s_cbranch_scc1 .Lg4y_a
	s_cmp_eq_u32 s101, 1
	s_cbranch_scc1 .Lg4y_b
	s_waitcnt vmcnt(20)
	s_branch .Lg4y_d

.Lg4y_d:
	s_mov_b32 s101, 0
	s_waitcnt lgkmcnt(0)
	s_barrier
	s_setprio 1
	s_waitcnt lgkmcnt(0)
	v_mfma_f32_16x16x32_bf16 v[62:65], v[66:69], v[162:165], v[62:65]
	v_mfma_f32_16x16x32_bf16 v[54:57], v[86:89], v[162:165], v[54:57]
	v_mfma_f32_16x16x32_bf16 v[46:49], v[66:69], v[170:173], v[46:49]
	v_mfma_f32_16x16x32_bf16 v[42:45], v[86:89], v[170:173], v[42:45]
	v_mfma_f32_16x16x32_bf16 v[30:33], v[66:69], v[196:199], v[30:33]
	v_mfma_f32_16x16x32_bf16 v[26:29], v[86:89], v[196:199], v[26:29]
	v_mfma_f32_16x16x32_bf16 v[14:17], v[66:69], v[204:207], v[14:17]
	v_mfma_f32_16x16x32_bf16 v[10:13], v[86:89], v[204:207], v[10:13]
	v_mfma_f32_16x16x32_bf16 v[62:65], v[70:73], v[166:169], v[62:65]
	v_mfma_f32_16x16x32_bf16 v[54:57], v[106:109], v[166:169], v[54:57]
	v_mfma_f32_16x16x32_bf16 v[46:49], v[70:73], v[174:177], v[46:49]
	v_mfma_f32_16x16x32_bf16 v[42:45], v[106:109], v[174:177], v[42:45]
	v_mfma_f32_16x16x32_bf16 v[30:33], v[70:73], v[200:203], v[30:33]
	v_mfma_f32_16x16x32_bf16 v[26:29], v[106:109], v[200:203], v[26:29]
	v_mfma_f32_16x16x32_bf16 v[14:17], v[70:73], v[208:211], v[14:17]
	v_mfma_f32_16x16x32_bf16 v[10:13], v[106:109], v[208:211], v[10:13]
	s_setprio 0
	s_setprio 1
	v_mfma_f32_16x16x32_bf16 v[58:61], v[146:149], v[162:165], v[58:61]
	v_mfma_f32_16x16x32_bf16 v[50:53], v[154:157], v[162:165], v[50:53]
	v_mfma_f32_16x16x32_bf16 v[38:41], v[146:149], v[170:173], v[38:41]
	v_mfma_f32_16x16x32_bf16 v[34:37], v[154:157], v[170:173], v[34:37]
	v_mfma_f32_16x16x32_bf16 v[22:25], v[146:149], v[196:199], v[22:25]
	v_mfma_f32_16x16x32_bf16 v[18:21], v[154:157], v[196:199], v[18:21]
	v_mfma_f32_16x16x32_bf16 v[6:9], v[146:149], v[204:207], v[6:9]
	v_mfma_f32_16x16x32_bf16 v[2:5], v[154:157], v[204:207], v[2:5]
	v_mfma_f32_16x16x32_bf16 v[58:61], v[150:153], v[166:169], v[58:61]
	v_mfma_f32_16x16x32_bf16 v[50:53], v[158:161], v[166:169], v[50:53]
	v_mfma_f32_16x16x32_bf16 v[38:41], v[150:153], v[174:177], v[38:41]
	v_mfma_f32_16x16x32_bf16 v[34:37], v[158:161], v[174:177], v[34:37]
	v_mfma_f32_16x16x32_bf16 v[22:25], v[150:153], v[200:203], v[22:25]
	v_mfma_f32_16x16x32_bf16 v[18:21], v[158:161], v[200:203], v[18:21]
	v_mfma_f32_16x16x32_bf16 v[6:9], v[150:153], v[208:211], v[6:9]
	v_mfma_f32_16x16x32_bf16 v[2:5], v[158:161], v[208:211], v[2:5]
	s_setprio 0
	s_barrier
	s_add_i32 s37, 0, 0x18000
	s_add_i32 s39, 0, 0x1c000
	v_add_u32_e32 v106, s37, v213
	v_add_u32_e32 v158, s39, v213
	ds_read_b128 v[66:69], v106
	ds_read_b128 v[70:73], v106 offset:1024
	ds_read_b128 v[86:89], v106 offset:2048
	ds_read_b128 v[106:109], v106 offset:3072
	ds_read_b128 v[146:149], v158
	ds_read_b128 v[150:153], v158 offset:1024
	ds_read_b128 v[154:157], v158 offset:2048
	ds_read_b128 v[158:161], v158 offset:3072
	s_add_u32 s44, s44, 0x40000
	s_addc_u32 s45, s45, 0
	s_mov_b32 m0, s56
	ds_read_b128 v[162:165], v221 offset:32768
	ds_read_b128 v[166:169], v221 offset:33792
	ds_read_b128 v[170:173], v221 offset:34816
	ds_read_b128 v[174:177], v221 offset:35840
	ds_read_b128 v[196:199], v221 offset:36864
	ds_read_b128 v[200:203], v221 offset:37888
	ds_read_b128 v[204:207], v221 offset:38912
	ds_read_b128 v[208:211], v221 offset:39936
	global_load_lds_dwordx4 v182, s[44:45]
	s_mov_b32 m0, s57
	s_nop 0
	global_load_lds_dwordx4 v186, s[44:45]
	s_waitcnt vmcnt(8)
	s_waitcnt lgkmcnt(0)
	s_barrier
	s_setprio 1
	s_waitcnt lgkmcnt(0)
	v_mfma_f32_16x16x32_bf16 v[142:145], v[66:69], v[162:165], v[142:145]
	v_mfma_f32_16x16x32_bf16 v[134:137], v[86:89], v[162:165], v[134:137]
	v_mfma_f32_16x16x32_bf16 v[126:129], v[66:69], v[170:173], v[126:129]
	v_mfma_f32_16x16x32_bf16 v[122:125], v[86:89], v[170:173], v[122:125]
	v_mfma_f32_16x16x32_bf16 v[110:113], v[66:69], v[196:199], v[110:113]
	v_mfma_f32_16x16x32_bf16 v[102:105], v[86:89], v[196:199], v[102:105]
	v_mfma_f32_16x16x32_bf16 v[90:93], v[66:69], v[204:207], v[90:93]
	v_mfma_f32_16x16x32_bf16 v[82:85], v[86:89], v[204:207], v[82:85]
	v_mfma_f32_16x16x32_bf16 v[142:145], v[70:73], v[166:169], v[142:145]
	v_mfma_f32_16x16x32_bf16 v[134:137], v[106:109], v[166:169], v[134:137]
	v_mfma_f32_16x16x32_bf16 v[126:129], v[70:73], v[174:177], v[126:129]
	v_mfma_f32_16x16x32_bf16 v[122:125], v[106:109], v[174:177], v[122:125]
	v_mfma_f32_16x16x32_bf16 v[110:113], v[70:73], v[200:203], v[110:113]
	v_mfma_f32_16x16x32_bf16 v[102:105], v[106:109], v[200:203], v[102:105]
	v_mfma_f32_16x16x32_bf16 v[90:93], v[70:73], v[208:211], v[90:93]
	v_mfma_f32_16x16x32_bf16 v[82:85], v[106:109], v[208:211], v[82:85]
	s_setprio 0
	s_setprio 1
	v_mfma_f32_16x16x32_bf16 v[138:141], v[146:149], v[162:165], v[138:141]
	v_mfma_f32_16x16x32_bf16 v[130:133], v[154:157], v[162:165], v[130:133]
	v_mfma_f32_16x16x32_bf16 v[118:121], v[146:149], v[170:173], v[118:121]
	v_mfma_f32_16x16x32_bf16 v[114:117], v[154:157], v[170:173], v[114:117]
	v_mfma_f32_16x16x32_bf16 v[98:101], v[146:149], v[196:199], v[98:101]
	v_mfma_f32_16x16x32_bf16 v[94:97], v[154:157], v[196:199], v[94:97]
	v_mfma_f32_16x16x32_bf16 v[78:81], v[146:149], v[204:207], v[78:81]
	v_mfma_f32_16x16x32_bf16 v[74:77], v[154:157], v[204:207], v[74:77]
	v_mfma_f32_16x16x32_bf16 v[138:141], v[150:153], v[166:169], v[138:141]
	v_mfma_f32_16x16x32_bf16 v[130:133], v[158:161], v[166:169], v[130:133]
	v_mfma_f32_16x16x32_bf16 v[118:121], v[150:153], v[174:177], v[118:121]
	v_mfma_f32_16x16x32_bf16 v[114:117], v[158:161], v[174:177], v[114:117]
	v_mfma_f32_16x16x32_bf16 v[98:101], v[150:153], v[200:203], v[98:101]
	v_mfma_f32_16x16x32_bf16 v[94:97], v[158:161], v[200:203], v[94:97]
	v_mfma_f32_16x16x32_bf16 v[78:81], v[150:153], v[208:211], v[78:81]
	v_mfma_f32_16x16x32_bf16 v[74:77], v[158:161], v[208:211], v[74:77]
	s_setprio 0
	s_barrier
	s_add_i32 s37, s37, s53
	s_mov_b32 m0, s37
	ds_read_b128 v[162:165], v221 offset:49152
	ds_read_b128 v[166:169], v221 offset:50176
	ds_read_b128 v[170:173], v221 offset:51200
	ds_read_b128 v[174:177], v221 offset:52224
	ds_read_b128 v[196:199], v221 offset:53248
	ds_read_b128 v[200:203], v221 offset:54272
	ds_read_b128 v[204:207], v221 offset:55296
	ds_read_b128 v[208:211], v221 offset:56320
	s_add_u32 s98, s10, 0x80
	s_addc_u32 s99, s11, 0
	global_load_lds_dwordx4 v184, s[98:99]
	s_add_i32 m0, s37, 0x2000
	s_add_u32 s10, s10, 0x40080
	s_addc_u32 s11, s11, 0
	s_add_i32 s37, s39, s53
	global_load_lds_dwordx4 v188, s[98:99]
	s_mov_b32 m0, s37
	s_nop 0
	global_load_lds_dwordx4 v184, s[10:11]
	s_add_i32 m0, s37, 0x2000
	s_nop 0
	global_load_lds_dwordx4 v188, s[10:11]
	s_add_u32 s98, s44, 0xfffc0080
	s_addc_u32 s99, s45, -1
	s_mov_b32 m0, s60
	s_nop 0
	global_load_lds_dwordx4 v182, s[98:99]
	s_mov_b32 m0, s61
	s_nop 0
	global_load_lds_dwordx4 v186, s[98:99]
	s_waitcnt vmcnt(8)
	s_waitcnt lgkmcnt(0)
	s_barrier
	s_setprio 1
	s_waitcnt lgkmcnt(0)
	v_mfma_f32_16x16x32_bf16 v[62:65], v[66:69], v[162:165], v[62:65]
	v_mfma_f32_16x16x32_bf16 v[54:57], v[86:89], v[162:165], v[54:57]
	v_mfma_f32_16x16x32_bf16 v[46:49], v[66:69], v[170:173], v[46:49]
	v_mfma_f32_16x16x32_bf16 v[42:45], v[86:89], v[170:173], v[42:45]
	v_mfma_f32_16x16x32_bf16 v[30:33], v[66:69], v[196:199], v[30:33]
	v_mfma_f32_16x16x32_bf16 v[26:29], v[86:89], v[196:199], v[26:29]
	v_mfma_f32_16x16x32_bf16 v[14:17], v[66:69], v[204:207], v[14:17]
	v_mfma_f32_16x16x32_bf16 v[10:13], v[86:89], v[204:207], v[10:13]
	v_mfma_f32_16x16x32_bf16 v[62:65], v[70:73], v[166:169], v[62:65]
	v_mfma_f32_16x16x32_bf16 v[54:57], v[106:109], v[166:169], v[54:57]
	v_mfma_f32_16x16x32_bf16 v[46:49], v[70:73], v[174:177], v[46:49]
	v_mfma_f32_16x16x32_bf16 v[42:45], v[106:109], v[174:177], v[42:45]
	v_mfma_f32_16x16x32_bf16 v[30:33], v[70:73], v[200:203], v[30:33]
	v_mfma_f32_16x16x32_bf16 v[26:29], v[106:109], v[200:203], v[26:29]
	v_mfma_f32_16x16x32_bf16 v[14:17], v[70:73], v[208:211], v[14:17]
	v_mfma_f32_16x16x32_bf16 v[10:13], v[106:109], v[208:211], v[10:13]
	s_setprio 0
	s_setprio 1
	v_mfma_f32_16x16x32_bf16 v[58:61], v[146:149], v[162:165], v[58:61]
	v_mfma_f32_16x16x32_bf16 v[50:53], v[154:157], v[162:165], v[50:53]
	v_mfma_f32_16x16x32_bf16 v[38:41], v[146:149], v[170:173], v[38:41]
	v_mfma_f32_16x16x32_bf16 v[34:37], v[154:157], v[170:173], v[34:37]
	v_mfma_f32_16x16x32_bf16 v[22:25], v[146:149], v[196:199], v[22:25]
	v_mfma_f32_16x16x32_bf16 v[18:21], v[154:157], v[196:199], v[18:21]
	v_mfma_f32_16x16x32_bf16 v[6:9], v[146:149], v[204:207], v[6:9]
	v_mfma_f32_16x16x32_bf16 v[2:5], v[154:157], v[204:207], v[2:5]
	v_mfma_f32_16x16x32_bf16 v[58:61], v[150:153], v[166:169], v[58:61]
	v_mfma_f32_16x16x32_bf16 v[50:53], v[158:161], v[166:169], v[50:53]
	v_mfma_f32_16x16x32_bf16 v[38:41], v[150:153], v[174:177], v[38:41]
	v_mfma_f32_16x16x32_bf16 v[34:37], v[158:161], v[174:177], v[34:37]
	v_mfma_f32_16x16x32_bf16 v[22:25], v[150:153], v[200:203], v[22:25]
	v_mfma_f32_16x16x32_bf16 v[18:21], v[158:161], v[200:203], v[18:21]
	v_mfma_f32_16x16x32_bf16 v[6:9], v[150:153], v[208:211], v[6:9]
	v_mfma_f32_16x16x32_bf16 v[2:5], v[158:161], v[208:211], v[2:5]
	s_setprio 0
	s_barrier
	s_add_i32 s22, s22, 2
	s_add_u32 s8, s8, 0x100
	s_addc_u32 s9, s9, 0
	s_add_u32 s5, s5, 0x100
	s_addc_u32 s7, s7, 0
	s_cmp_gt_u32 s22, 13
	s_cbranch_scc0 .LBB0_991
	s_and_b64 vcc, exec, s[30:31]
	s_cbranch_vccz .LBB0_994

.LBB0_1037:
	s_or_b64 exec, exec, s[6:7]
	s_andn2_b64 vcc, exec, s[100:101]
	s_mov_b32 s101, 1
	s_cbranch_vccnz .Lcpe4_skip
	s_waitcnt vmcnt(8)
	global_store_dwordx4 v[248:249], v[146:149], off nt
	global_store_dwordx4 v[250:251], v[154:157], off nt
	global_store_dwordx4 v[252:253], v[150:153], off nt
	global_store_dwordx4 v[254:255], v[158:161], off nt
	s_mov_b32 s101, 2
